# S5 end-state pass: scan rewritten by hand, one copy per direction, unpack + four FMAs per step
# speedup vs baseline: 1.0122x; 1.0040x over previous
.LBB0_322:
.LBB0_323:
.Lm0_loopctl:
	s_xor_b64 s[12:13], s[10:11], -1
	s_mov_b64 s[10:11], 0
	s_and_b64 vcc, exec, s[12:13]
	s_mov_b64 s[12:13], s[8:9]
	s_cbranch_vccnz .LBB0_320
.LBB0_324:
	v_cndmask_b32_e64 v45, v23, v19, s[12:13]
	v_cndmask_b32_e64 v44, v22, v18, s[12:13]
	v_cndmask_b32_e64 v43, v21, v17, s[12:13]
	v_cndmask_b32_e64 v42, v20, v16, s[12:13]
	s_mov_b64 s[12:13], -1
	s_andn2_b64 vcc, exec, s[8:9]
	s_waitcnt vmcnt(0) lgkmcnt(0)
	v_mfma_f32_32x32x16_bf16 v[0:15], v[42:45], v[26:29], 0
	s_nop 11
	v_cvt_pk_bf16_f32 v0, v0, v1
	v_cvt_pk_bf16_f32 v1, v2, v3
	v_cvt_pk_bf16_f32 v2, v4, v5
	v_cvt_pk_bf16_f32 v3, v6, v7
	v_cvt_pk_bf16_f32 v4, v8, v9
	v_cvt_pk_bf16_f32 v5, v10, v11
	v_cvt_pk_bf16_f32 v6, v12, v13
	v_cvt_pk_bf16_f32 v7, v14, v15
	ds_write2_b64 v76, v[0:1], v[2:3] offset1:2
	ds_write2_b64 v76, v[4:5], v[6:7] offset0:4 offset1:6
	v_mfma_f32_32x32x16_bf16 v[0:15], v[42:45], v[30:33], 0
	s_nop 11
	v_cvt_pk_bf16_f32 v0, v0, v1
	v_cvt_pk_bf16_f32 v1, v2, v3
	v_cvt_pk_bf16_f32 v2, v4, v5
	v_cvt_pk_bf16_f32 v3, v6, v7
	v_add_u32_e32 v4, 0x800, v76
	ds_write2_b64 v4, v[0:1], v[2:3] offset0:64 offset1:66
	v_cvt_pk_bf16_f32 v0, v8, v9
	v_cvt_pk_bf16_f32 v1, v10, v11
	v_cvt_pk_bf16_f32 v2, v12, v13
	v_cvt_pk_bf16_f32 v3, v14, v15
	ds_write2_b64 v4, v[0:1], v[2:3] offset0:68 offset1:70
	v_mfma_f32_32x32x16_bf16 v[0:15], v[42:45], v[34:37], 0
	s_nop 11
	v_cvt_pk_bf16_f32 v0, v0, v1
	v_cvt_pk_bf16_f32 v1, v2, v3
	v_cvt_pk_bf16_f32 v2, v4, v5
	v_cvt_pk_bf16_f32 v3, v6, v7
	v_add_u32_e32 v4, 0x1000, v76
	ds_write2_b64 v4, v[0:1], v[2:3] offset0:128 offset1:130
	v_cvt_pk_bf16_f32 v0, v8, v9
	v_cvt_pk_bf16_f32 v1, v10, v11
	v_cvt_pk_bf16_f32 v2, v12, v13
	v_cvt_pk_bf16_f32 v3, v14, v15
	ds_write2_b64 v4, v[0:1], v[2:3] offset0:132 offset1:134
	v_mfma_f32_32x32x16_bf16 v[0:15], v[42:45], v[38:41], 0
	s_nop 11
	v_cvt_pk_bf16_f32 v0, v0, v1
	v_cvt_pk_bf16_f32 v1, v2, v3
	v_cvt_pk_bf16_f32 v2, v4, v5
	v_cvt_pk_bf16_f32 v3, v6, v7
	v_add_u32_e32 v4, 0x1800, v76
	ds_write2_b64 v4, v[0:1], v[2:3] offset0:192 offset1:194
	v_cvt_pk_bf16_f32 v0, v8, v9
	v_cvt_pk_bf16_f32 v1, v10, v11
	v_cvt_pk_bf16_f32 v2, v12, v13
	v_cvt_pk_bf16_f32 v3, v14, v15
	ds_write2_b64 v4, v[0:1], v[2:3] offset0:196 offset1:198
	s_waitcnt lgkmcnt(0)
	v_add_u32_e32 v0, s16, v71
	ds_read_b128 v[12:15], v0
	ds_read_b128 v[4:7], v0 offset:16
	v_add_u32_e32 v1, s17, v71
	ds_read_b128 v[50:53], v1 offset:5120
	ds_read_b128 v[46:49], v1
	ds_read_b128 v[42:45], v1 offset:16
	ds_read_b128 v[54:57], v1 offset:5136
	ds_read_b128 v[8:11], v0 offset:5120
	ds_read_b128 v[0:3], v0 offset:5136
	s_waitcnt lgkmcnt(0)
	s_cbranch_vccnz .Lm0_fwd
	v_and_b32_e32 v77, 0xffff0000, v7
	v_and_b32_e32 v78, 0xffff0000, v3
	v_fma_f32 v77, -v25, v67, v77
	v_fma_f32 v78, v25, v66, v78
	v_fma_f32 v79, v24, v66, v77
	v_fma_f32 v80, v24, v67, v78
	v_lshlrev_b32_e32 v77, 16, v7
	v_lshlrev_b32_e32 v78, 16, v3
	v_fma_f32 v77, -v25, v80, v77
	v_fma_f32 v78, v25, v79, v78
	v_fma_f32 v66, v24, v79, v77
	v_fma_f32 v67, v24, v80, v78
	v_and_b32_e32 v77, 0xffff0000, v6
	v_and_b32_e32 v78, 0xffff0000, v2
	v_fma_f32 v77, -v25, v67, v77
	v_fma_f32 v78, v25, v66, v78
	v_fma_f32 v79, v24, v66, v77
	v_fma_f32 v80, v24, v67, v78
	v_lshlrev_b32_e32 v77, 16, v6
	v_lshlrev_b32_e32 v78, 16, v2
	v_fma_f32 v77, -v25, v80, v77
	v_fma_f32 v78, v25, v79, v78
	v_fma_f32 v66, v24, v79, v77
	v_fma_f32 v67, v24, v80, v78
	v_and_b32_e32 v77, 0xffff0000, v5
	v_and_b32_e32 v78, 0xffff0000, v1
	v_fma_f32 v77, -v25, v67, v77
	v_fma_f32 v78, v25, v66, v78
	v_fma_f32 v79, v24, v66, v77
	v_fma_f32 v80, v24, v67, v78
	v_lshlrev_b32_e32 v77, 16, v5
	v_lshlrev_b32_e32 v78, 16, v1
	v_fma_f32 v77, -v25, v80, v77
	v_fma_f32 v78, v25, v79, v78
	v_fma_f32 v66, v24, v79, v77
	v_fma_f32 v67, v24, v80, v78
	v_and_b32_e32 v77, 0xffff0000, v4
	v_and_b32_e32 v78, 0xffff0000, v0
	v_fma_f32 v77, -v25, v67, v77
	v_fma_f32 v78, v25, v66, v78
	v_fma_f32 v79, v24, v66, v77
	v_fma_f32 v80, v24, v67, v78
	v_lshlrev_b32_e32 v77, 16, v4
	v_lshlrev_b32_e32 v78, 16, v0
	v_fma_f32 v77, -v25, v80, v77
	v_fma_f32 v78, v25, v79, v78
	v_fma_f32 v66, v24, v79, v77
	v_fma_f32 v67, v24, v80, v78
	v_and_b32_e32 v77, 0xffff0000, v15
	v_and_b32_e32 v78, 0xffff0000, v11
	v_fma_f32 v77, -v25, v67, v77
	v_fma_f32 v78, v25, v66, v78
	v_fma_f32 v79, v24, v66, v77
	v_fma_f32 v80, v24, v67, v78
	v_lshlrev_b32_e32 v77, 16, v15
	v_lshlrev_b32_e32 v78, 16, v11
	v_fma_f32 v77, -v25, v80, v77
	v_fma_f32 v78, v25, v79, v78
	v_fma_f32 v66, v24, v79, v77
	v_fma_f32 v67, v24, v80, v78
	v_and_b32_e32 v77, 0xffff0000, v14
	v_and_b32_e32 v78, 0xffff0000, v10
	v_fma_f32 v77, -v25, v67, v77
	v_fma_f32 v78, v25, v66, v78
	v_fma_f32 v79, v24, v66, v77
	v_fma_f32 v80, v24, v67, v78
	v_lshlrev_b32_e32 v77, 16, v14
	v_lshlrev_b32_e32 v78, 16, v10
	v_fma_f32 v77, -v25, v80, v77
	v_fma_f32 v78, v25, v79, v78
	v_fma_f32 v66, v24, v79, v77
	v_fma_f32 v67, v24, v80, v78
	v_and_b32_e32 v77, 0xffff0000, v13
	v_and_b32_e32 v78, 0xffff0000, v9
	v_fma_f32 v77, -v25, v67, v77
	v_fma_f32 v78, v25, v66, v78
	v_fma_f32 v79, v24, v66, v77
	v_fma_f32 v80, v24, v67, v78
	v_lshlrev_b32_e32 v77, 16, v13
	v_lshlrev_b32_e32 v78, 16, v9
	v_fma_f32 v77, -v25, v80, v77
	v_fma_f32 v78, v25, v79, v78
	v_fma_f32 v66, v24, v79, v77
	v_fma_f32 v67, v24, v80, v78
	v_and_b32_e32 v77, 0xffff0000, v12
	v_and_b32_e32 v78, 0xffff0000, v8
	v_fma_f32 v77, -v25, v67, v77
	v_fma_f32 v78, v25, v66, v78
	v_fma_f32 v79, v24, v66, v77
	v_fma_f32 v80, v24, v67, v78
	v_lshlrev_b32_e32 v77, 16, v12
	v_lshlrev_b32_e32 v78, 16, v8
	v_fma_f32 v77, -v25, v80, v77
	v_fma_f32 v78, v25, v79, v78
	v_fma_f32 v66, v24, v79, v77
	v_fma_f32 v67, v24, v80, v78
	v_and_b32_e32 v77, 0xffff0000, v45
	v_and_b32_e32 v78, 0xffff0000, v57
	v_fma_f32 v77, -v25, v67, v77
	v_fma_f32 v78, v25, v66, v78
	v_fma_f32 v79, v24, v66, v77
	v_fma_f32 v80, v24, v67, v78
	v_lshlrev_b32_e32 v77, 16, v45
	v_lshlrev_b32_e32 v78, 16, v57
	v_fma_f32 v77, -v25, v80, v77
	v_fma_f32 v78, v25, v79, v78
	v_fma_f32 v66, v24, v79, v77
	v_fma_f32 v67, v24, v80, v78
	v_and_b32_e32 v77, 0xffff0000, v44
	v_and_b32_e32 v78, 0xffff0000, v56
	v_fma_f32 v77, -v25, v67, v77
	v_fma_f32 v78, v25, v66, v78
	v_fma_f32 v79, v24, v66, v77
	v_fma_f32 v80, v24, v67, v78
	v_lshlrev_b32_e32 v77, 16, v44
	v_lshlrev_b32_e32 v78, 16, v56
	v_fma_f32 v77, -v25, v80, v77
	v_fma_f32 v78, v25, v79, v78
	v_fma_f32 v66, v24, v79, v77
	v_fma_f32 v67, v24, v80, v78
	v_and_b32_e32 v77, 0xffff0000, v43
	v_and_b32_e32 v78, 0xffff0000, v55
	v_fma_f32 v77, -v25, v67, v77
	v_fma_f32 v78, v25, v66, v78
	v_fma_f32 v79, v24, v66, v77
	v_fma_f32 v80, v24, v67, v78
	v_lshlrev_b32_e32 v77, 16, v43
	v_lshlrev_b32_e32 v78, 16, v55
	v_fma_f32 v77, -v25, v80, v77
	v_fma_f32 v78, v25, v79, v78
	v_fma_f32 v66, v24, v79, v77
	v_fma_f32 v67, v24, v80, v78
	v_and_b32_e32 v77, 0xffff0000, v42
	v_and_b32_e32 v78, 0xffff0000, v54
	v_fma_f32 v77, -v25, v67, v77
	v_fma_f32 v78, v25, v66, v78
	v_fma_f32 v79, v24, v66, v77
	v_fma_f32 v80, v24, v67, v78
	v_lshlrev_b32_e32 v77, 16, v42
	v_lshlrev_b32_e32 v78, 16, v54
	v_fma_f32 v77, -v25, v80, v77
	v_fma_f32 v78, v25, v79, v78
	v_fma_f32 v66, v24, v79, v77
	v_fma_f32 v67, v24, v80, v78
	v_and_b32_e32 v77, 0xffff0000, v49
	v_and_b32_e32 v78, 0xffff0000, v53
	v_fma_f32 v77, -v25, v67, v77
	v_fma_f32 v78, v25, v66, v78
	v_fma_f32 v79, v24, v66, v77
	v_fma_f32 v80, v24, v67, v78
	v_lshlrev_b32_e32 v77, 16, v49
	v_lshlrev_b32_e32 v78, 16, v53
	v_fma_f32 v77, -v25, v80, v77
	v_fma_f32 v78, v25, v79, v78
	v_fma_f32 v66, v24, v79, v77
	v_fma_f32 v67, v24, v80, v78
	v_and_b32_e32 v77, 0xffff0000, v48
	v_and_b32_e32 v78, 0xffff0000, v52
	v_fma_f32 v77, -v25, v67, v77
	v_fma_f32 v78, v25, v66, v78
	v_fma_f32 v79, v24, v66, v77
	v_fma_f32 v80, v24, v67, v78
	v_lshlrev_b32_e32 v77, 16, v48
	v_lshlrev_b32_e32 v78, 16, v52
	v_fma_f32 v77, -v25, v80, v77
	v_fma_f32 v78, v25, v79, v78
	v_fma_f32 v66, v24, v79, v77
	v_fma_f32 v67, v24, v80, v78
	v_and_b32_e32 v77, 0xffff0000, v47
	v_and_b32_e32 v78, 0xffff0000, v51
	v_fma_f32 v77, -v25, v67, v77
	v_fma_f32 v78, v25, v66, v78
	v_fma_f32 v79, v24, v66, v77
	v_fma_f32 v80, v24, v67, v78
	v_lshlrev_b32_e32 v77, 16, v47
	v_lshlrev_b32_e32 v78, 16, v51
	v_fma_f32 v77, -v25, v80, v77
	v_fma_f32 v78, v25, v79, v78
	v_fma_f32 v66, v24, v79, v77
	v_fma_f32 v67, v24, v80, v78
	v_and_b32_e32 v77, 0xffff0000, v46
	v_and_b32_e32 v78, 0xffff0000, v50
	v_fma_f32 v77, -v25, v67, v77
	v_fma_f32 v78, v25, v66, v78
	v_fma_f32 v79, v24, v66, v77
	v_fma_f32 v80, v24, v67, v78
	v_lshlrev_b32_e32 v77, 16, v46
	v_lshlrev_b32_e32 v78, 16, v50
	v_fma_f32 v77, -v25, v80, v77
	v_fma_f32 v78, v25, v79, v78
	v_fma_f32 v66, v24, v79, v77
	v_fma_f32 v67, v24, v80, v78
	s_branch .Lm0_loopctl
.Lm0_fwd:
	v_lshlrev_b32_e32 v77, 16, v12
	v_lshlrev_b32_e32 v78, 16, v8
	v_fma_f32 v77, -v25, v67, v77
	v_fma_f32 v78, v25, v66, v78
	v_fma_f32 v79, v24, v66, v77
	v_fma_f32 v80, v24, v67, v78
	v_and_b32_e32 v77, 0xffff0000, v12
	v_and_b32_e32 v78, 0xffff0000, v8
	v_fma_f32 v77, -v25, v80, v77
	v_fma_f32 v78, v25, v79, v78
	v_fma_f32 v66, v24, v79, v77
	v_fma_f32 v67, v24, v80, v78
	v_lshlrev_b32_e32 v77, 16, v13
	v_lshlrev_b32_e32 v78, 16, v9
	v_fma_f32 v77, -v25, v67, v77
	v_fma_f32 v78, v25, v66, v78
	v_fma_f32 v79, v24, v66, v77
	v_fma_f32 v80, v24, v67, v78
	v_and_b32_e32 v77, 0xffff0000, v13
	v_and_b32_e32 v78, 0xffff0000, v9
	v_fma_f32 v77, -v25, v80, v77
	v_fma_f32 v78, v25, v79, v78
	v_fma_f32 v66, v24, v79, v77
	v_fma_f32 v67, v24, v80, v78
	v_lshlrev_b32_e32 v77, 16, v14
	v_lshlrev_b32_e32 v78, 16, v10
	v_fma_f32 v77, -v25, v67, v77
	v_fma_f32 v78, v25, v66, v78
	v_fma_f32 v79, v24, v66, v77
	v_fma_f32 v80, v24, v67, v78
	v_and_b32_e32 v77, 0xffff0000, v14
	v_and_b32_e32 v78, 0xffff0000, v10
	v_fma_f32 v77, -v25, v80, v77
	v_fma_f32 v78, v25, v79, v78
	v_fma_f32 v66, v24, v79, v77
	v_fma_f32 v67, v24, v80, v78
	v_lshlrev_b32_e32 v77, 16, v15
	v_lshlrev_b32_e32 v78, 16, v11
	v_fma_f32 v77, -v25, v67, v77
	v_fma_f32 v78, v25, v66, v78
	v_fma_f32 v79, v24, v66, v77
	v_fma_f32 v80, v24, v67, v78
	v_and_b32_e32 v77, 0xffff0000, v15
	v_and_b32_e32 v78, 0xffff0000, v11
	v_fma_f32 v77, -v25, v80, v77
	v_fma_f32 v78, v25, v79, v78
	v_fma_f32 v66, v24, v79, v77
	v_fma_f32 v67, v24, v80, v78
	v_lshlrev_b32_e32 v77, 16, v4
	v_lshlrev_b32_e32 v78, 16, v0
	v_fma_f32 v77, -v25, v67, v77
	v_fma_f32 v78, v25, v66, v78
	v_fma_f32 v79, v24, v66, v77
	v_fma_f32 v80, v24, v67, v78
	v_and_b32_e32 v77, 0xffff0000, v4
	v_and_b32_e32 v78, 0xffff0000, v0
	v_fma_f32 v77, -v25, v80, v77
	v_fma_f32 v78, v25, v79, v78
	v_fma_f32 v66, v24, v79, v77
	v_fma_f32 v67, v24, v80, v78
	v_lshlrev_b32_e32 v77, 16, v5
	v_lshlrev_b32_e32 v78, 16, v1
	v_fma_f32 v77, -v25, v67, v77
	v_fma_f32 v78, v25, v66, v78
	v_fma_f32 v79, v24, v66, v77
	v_fma_f32 v80, v24, v67, v78
	v_and_b32_e32 v77, 0xffff0000, v5
	v_and_b32_e32 v78, 0xffff0000, v1
	v_fma_f32 v77, -v25, v80, v77
	v_fma_f32 v78, v25, v79, v78
	v_fma_f32 v66, v24, v79, v77
	v_fma_f32 v67, v24, v80, v78
	v_lshlrev_b32_e32 v77, 16, v6
	v_lshlrev_b32_e32 v78, 16, v2
	v_fma_f32 v77, -v25, v67, v77
	v_fma_f32 v78, v25, v66, v78
	v_fma_f32 v79, v24, v66, v77
	v_fma_f32 v80, v24, v67, v78
	v_and_b32_e32 v77, 0xffff0000, v6
	v_and_b32_e32 v78, 0xffff0000, v2
	v_fma_f32 v77, -v25, v80, v77
	v_fma_f32 v78, v25, v79, v78
	v_fma_f32 v66, v24, v79, v77
	v_fma_f32 v67, v24, v80, v78
	v_lshlrev_b32_e32 v77, 16, v7
	v_lshlrev_b32_e32 v78, 16, v3
	v_fma_f32 v77, -v25, v67, v77
	v_fma_f32 v78, v25, v66, v78
	v_fma_f32 v79, v24, v66, v77
	v_fma_f32 v80, v24, v67, v78
	v_and_b32_e32 v77, 0xffff0000, v7
	v_and_b32_e32 v78, 0xffff0000, v3
	v_fma_f32 v77, -v25, v80, v77
	v_fma_f32 v78, v25, v79, v78
	v_fma_f32 v66, v24, v79, v77
	v_fma_f32 v67, v24, v80, v78
	v_lshlrev_b32_e32 v77, 16, v46
	v_lshlrev_b32_e32 v78, 16, v50
	v_fma_f32 v77, -v25, v67, v77
	v_fma_f32 v78, v25, v66, v78
	v_fma_f32 v79, v24, v66, v77
	v_fma_f32 v80, v24, v67, v78
	v_and_b32_e32 v77, 0xffff0000, v46
	v_and_b32_e32 v78, 0xffff0000, v50
	v_fma_f32 v77, -v25, v80, v77
	v_fma_f32 v78, v25, v79, v78
	v_fma_f32 v66, v24, v79, v77
	v_fma_f32 v67, v24, v80, v78
	v_lshlrev_b32_e32 v77, 16, v47
	v_lshlrev_b32_e32 v78, 16, v51
	v_fma_f32 v77, -v25, v67, v77
	v_fma_f32 v78, v25, v66, v78
	v_fma_f32 v79, v24, v66, v77
	v_fma_f32 v80, v24, v67, v78
	v_and_b32_e32 v77, 0xffff0000, v47
	v_and_b32_e32 v78, 0xffff0000, v51
	v_fma_f32 v77, -v25, v80, v77
	v_fma_f32 v78, v25, v79, v78
	v_fma_f32 v66, v24, v79, v77
	v_fma_f32 v67, v24, v80, v78
	v_lshlrev_b32_e32 v77, 16, v48
	v_lshlrev_b32_e32 v78, 16, v52
	v_fma_f32 v77, -v25, v67, v77
	v_fma_f32 v78, v25, v66, v78
	v_fma_f32 v79, v24, v66, v77
	v_fma_f32 v80, v24, v67, v78
	v_and_b32_e32 v77, 0xffff0000, v48
	v_and_b32_e32 v78, 0xffff0000, v52
	v_fma_f32 v77, -v25, v80, v77
	v_fma_f32 v78, v25, v79, v78
	v_fma_f32 v66, v24, v79, v77
	v_fma_f32 v67, v24, v80, v78
	v_lshlrev_b32_e32 v77, 16, v49
	v_lshlrev_b32_e32 v78, 16, v53
	v_fma_f32 v77, -v25, v67, v77
	v_fma_f32 v78, v25, v66, v78
	v_fma_f32 v79, v24, v66, v77
	v_fma_f32 v80, v24, v67, v78
	v_and_b32_e32 v77, 0xffff0000, v49
	v_and_b32_e32 v78, 0xffff0000, v53
	v_fma_f32 v77, -v25, v80, v77
	v_fma_f32 v78, v25, v79, v78
	v_fma_f32 v66, v24, v79, v77
	v_fma_f32 v67, v24, v80, v78
	v_lshlrev_b32_e32 v77, 16, v42
	v_lshlrev_b32_e32 v78, 16, v54
	v_fma_f32 v77, -v25, v67, v77
	v_fma_f32 v78, v25, v66, v78
	v_fma_f32 v79, v24, v66, v77
	v_fma_f32 v80, v24, v67, v78
	v_and_b32_e32 v77, 0xffff0000, v42
	v_and_b32_e32 v78, 0xffff0000, v54
	v_fma_f32 v77, -v25, v80, v77
	v_fma_f32 v78, v25, v79, v78
	v_fma_f32 v66, v24, v79, v77
	v_fma_f32 v67, v24, v80, v78
	v_lshlrev_b32_e32 v77, 16, v43
	v_lshlrev_b32_e32 v78, 16, v55
	v_fma_f32 v77, -v25, v67, v77
	v_fma_f32 v78, v25, v66, v78
	v_fma_f32 v79, v24, v66, v77
	v_fma_f32 v80, v24, v67, v78
	v_and_b32_e32 v77, 0xffff0000, v43
	v_and_b32_e32 v78, 0xffff0000, v55
	v_fma_f32 v77, -v25, v80, v77
	v_fma_f32 v78, v25, v79, v78
	v_fma_f32 v66, v24, v79, v77
	v_fma_f32 v67, v24, v80, v78
	v_lshlrev_b32_e32 v77, 16, v44
	v_lshlrev_b32_e32 v78, 16, v56
	v_fma_f32 v77, -v25, v67, v77
	v_fma_f32 v78, v25, v66, v78
	v_fma_f32 v79, v24, v66, v77
	v_fma_f32 v80, v24, v67, v78
	v_and_b32_e32 v77, 0xffff0000, v44
	v_and_b32_e32 v78, 0xffff0000, v56
	v_fma_f32 v77, -v25, v80, v77
	v_fma_f32 v78, v25, v79, v78
	v_fma_f32 v66, v24, v79, v77
	v_fma_f32 v67, v24, v80, v78
	v_lshlrev_b32_e32 v77, 16, v45
	v_lshlrev_b32_e32 v78, 16, v57
	v_fma_f32 v77, -v25, v67, v77
	v_fma_f32 v78, v25, v66, v78
	v_fma_f32 v79, v24, v66, v77
	v_fma_f32 v80, v24, v67, v78
	v_and_b32_e32 v77, 0xffff0000, v45
	v_and_b32_e32 v78, 0xffff0000, v57
	v_fma_f32 v77, -v25, v80, v77
	v_fma_f32 v78, v25, v79, v78
	v_fma_f32 v66, v24, v79, v77
	v_fma_f32 v67, v24, v80, v78
	s_branch .Lm0_loopctl
